# grid barriers: every workgroup issues its own L2 writeback on arrival (early arrivers flush early) before the per-XCD leader flush
# baseline (speedup 1.0000x reference)
; __device__ __forceinline__ unsigned xb_ld(unsigned* p)              { return __hip_atomic_load(p, __ATOMIC_RELAXED, __HIP_MEMORY_SCOPE_AGENT); }
; __device__ __forceinline__ unsigned xb_add(unsigned* p, unsigned v) { return __hip_atomic_fetch_add(p, v, __ATOMIC_RELAXED, __HIP_MEMORY_SCOPE_AGENT); }
; __device__ __forceinline__ void xcd_barrier_complete(unsigned* bar, unsigned x, unsigned& nloc, unsigned& nx) {
;     const unsigned G = gridDim.x * gridDim.y * gridDim.z;
;     unsigned sum, cnt, mine, sp = 0u;
;     for (;;) {
;         sum = 0u; cnt = 0u; mine = 0u;
; #pragma unroll
;         for (unsigned j = 0; j < 16; ++j) { const unsigned c = xb_ld(&bar[XB_XCNT(j)]); sum += c; cnt += (c > 0u) ? 1u : 0u; mine = (j == x) ? c : mine; }
;         if (sum == G) break;
; __device__ __forceinline__ void xcd_barrier(const XcdBarrier& b) {
;     asm volatile("s_waitcnt vmcnt(0)" ::: "memory");
;     __syncthreads();
;     int t_ = threadIdx.x; asm volatile("" : "+v"(t_));
;     if (t_ == 0) {
;         unsigned* bar = b.bar;
;         __builtin_amdgcn_s_waitcnt(0);
;         unsigned nloc = b.st[0], nx = b.st[1];
;         if (nloc == 0u) { xcd_barrier_complete(bar, b.x, nloc, nx); b.st[0] = nloc; b.st[1] = nx; }
;         const unsigned old = xb_add(&bar[XB_XSUB(b.x)], 1u);
.LBB0_52:
	s_waitcnt vmcnt(0)
	v_mov_b32_e32 v0, v224
	s_barrier
	s_nop 0
	v_cmp_eq_u32_e32 vcc, 0, v0
	s_and_saveexec_b64 s[0:1], vcc
	s_cbranch_execz .LBB0_104
	s_add_i32 s2, 0, 0x20040
	v_mov_b32_e32 v0, s2
	buffer_wbl2 sc1
	s_waitcnt vmcnt(0) expcnt(0) lgkmcnt(0)
	ds_read_b32 v2, v0
	s_add_i32 s2, 0, 0x20044
	v_mov_b32_e32 v0, s2
	ds_read_b32 v0, v0
	s_waitcnt lgkmcnt(1)
	v_cmp_ne_u32_e32 vcc, 0, v2
	s_cbranch_vccnz .LBB0_68
	v_readlane_b32 s40, v251, 1
	v_readlane_b32 s42, v251, 3
	v_readlane_b32 s43, v251, 4
	s_add_u32 s2, s42, 0x4200
	s_addc_u32 s3, s43, 0
	s_add_u32 s8, s42, 0x4400
	s_addc_u32 s9, s43, 0
	s_add_u32 s10, s42, 0x4500
	s_addc_u32 s11, s43, 0
	s_add_u32 s12, s42, 0x4600
	s_addc_u32 s13, s43, 0
	s_add_u32 s14, s42, 0x4700
	s_addc_u32 s15, s43, 0
	s_add_u32 s16, s42, 0x4800
	s_addc_u32 s17, s43, 0
	s_add_u32 s18, s42, 0x4900
	s_addc_u32 s19, s43, 0
	s_add_u32 s20, s42, 0x4a00
	s_addc_u32 s21, s43, 0
	s_add_u32 s22, s42, 0x4b00
	s_addc_u32 s23, s43, 0
	s_add_u32 s24, s42, 0x4c00
	s_addc_u32 s25, s43, 0
	s_add_u32 s26, s42, 0x4d00
	s_addc_u32 s27, s43, 0
	s_add_u32 s28, s42, 0x4e00
	s_addc_u32 s29, s43, 0
	s_add_u32 s30, s42, 0x4f00
	s_addc_u32 s31, s43, 0
	s_add_u32 s34, s42, 0x5000
	s_addc_u32 s35, s43, 0
	s_add_u32 s36, s42, 0x5100
	s_addc_u32 s37, s43, 0
	s_add_u32 s38, s42, 0x5200
	s_addc_u32 s39, s43, 0
	s_mul_i32 s48, s73, s33
	v_readlane_b32 s41, v251, 2
	s_add_u32 s40, s42, 0x5300
	s_mul_i32 s48, s48, s72
	s_addc_u32 s41, s43, 0
	s_mov_b32 s49, 1
	v_mov_b32_e32 v16, 0
	s_branch .LBB0_56

; __device__ __forceinline__ unsigned xb_add(unsigned* p, unsigned v) { return __hip_atomic_fetch_add(p, v, __ATOMIC_RELAXED, __HIP_MEMORY_SCOPE_AGENT); }
; __device__ __forceinline__ void xcd_barrier(const XcdBarrier& b) {
;     asm volatile("s_waitcnt vmcnt(0)" ::: "memory");
;     __syncthreads();
;     int t_ = threadIdx.x; asm volatile("" : "+v"(t_));
;     if (t_ == 0) {
;         unsigned* bar = b.bar;
;         __builtin_amdgcn_s_waitcnt(0);
;         unsigned nloc = b.st[0], nx = b.st[1];
;         if (nloc == 0u) { xcd_barrier_complete(bar, b.x, nloc, nx); b.st[0] = nloc; b.st[1] = nx; }
;         const unsigned old = xb_add(&bar[XB_XSUB(b.x)], 1u);
.LBB0_394:
	s_waitcnt vmcnt(0)
	v_mov_b32_e32 v0, v224
	s_waitcnt vmcnt(0) lgkmcnt(0)
	s_barrier
	s_nop 0
	v_cmp_eq_u32_e32 vcc, 0, v0
	s_and_saveexec_b64 s[0:1], vcc
	s_cbranch_execz .LBB0_449
	v_readlane_b32 s2, v254, 41
	buffer_wbl2 sc1
	s_waitcnt vmcnt(0) expcnt(0) lgkmcnt(0)
	s_nop 0
	v_mov_b32_e32 v0, s2
	ds_read_b32 v3, v0
	v_readlane_b32 s2, v254, 42
	s_waitcnt lgkmcnt(0)
	v_cmp_ne_u32_e32 vcc, 0, v3
	v_mov_b32_e32 v0, s2
	ds_read_b32 v2, v0
	s_cbranch_vccnz .LBB0_410
	s_mov_b32 s2, 1
	s_branch .LBB0_398

; __device__ __forceinline__ unsigned xb_add(unsigned* p, unsigned v) { return __hip_atomic_fetch_add(p, v, __ATOMIC_RELAXED, __HIP_MEMORY_SCOPE_AGENT); }
; __device__ __forceinline__ void xcd_barrier(const XcdBarrier& b) {
;     asm volatile("s_waitcnt vmcnt(0)" ::: "memory");
;     __syncthreads();
;     int t_ = threadIdx.x; asm volatile("" : "+v"(t_));
;     if (t_ == 0) {
;         unsigned* bar = b.bar;
;         __builtin_amdgcn_s_waitcnt(0);
;         unsigned nloc = b.st[0], nx = b.st[1];
;         if (nloc == 0u) { xcd_barrier_complete(bar, b.x, nloc, nx); b.st[0] = nloc; b.st[1] = nx; }
;         const unsigned old = xb_add(&bar[XB_XSUB(b.x)], 1u);
.LBB0_606:
	s_waitcnt vmcnt(0)
	v_mov_b32_e32 v0, v224
	s_barrier
	s_nop 0
	v_cmp_eq_u32_e32 vcc, 0, v0
	s_and_saveexec_b64 s[0:1], vcc
	s_cbranch_execz .LBB0_658
	v_readlane_b32 s2, v254, 41
	buffer_wbl2 sc1
	s_waitcnt vmcnt(0) expcnt(0) lgkmcnt(0)
	s_nop 0
	v_mov_b32_e32 v0, s2
	ds_read_b32 v3, v0
	v_readlane_b32 s2, v254, 42
	s_waitcnt lgkmcnt(0)
	v_cmp_ne_u32_e32 vcc, 0, v3
	v_mov_b32_e32 v0, s2
	ds_read_b32 v2, v0
	s_cbranch_vccnz .LBB0_622
	s_mov_b32 s2, 1
	s_branch .LBB0_610

; __device__ __forceinline__ unsigned xb_add(unsigned* p, unsigned v) { return __hip_atomic_fetch_add(p, v, __ATOMIC_RELAXED, __HIP_MEMORY_SCOPE_AGENT); }
; __device__ __forceinline__ void xcd_barrier(const XcdBarrier& b) {
;     ...
;     if (t_ == 0) {
;         unsigned* bar = b.bar;
;         __builtin_amdgcn_s_waitcnt(0);
;         unsigned nloc = b.st[0], nx = b.st[1];
;         if (nloc == 0u) { xcd_barrier_complete(bar, b.x, nloc, nx); b.st[0] = nloc; b.st[1] = nx; }
;         const unsigned old = xb_add(&bar[XB_XSUB(b.x)], 1u);
.LBB0_931:
	v_readlane_b32 s2, v254, 41
	buffer_wbl2 sc1
	s_waitcnt vmcnt(0) expcnt(0) lgkmcnt(0)
	s_nop 0
	v_mov_b32_e32 v0, s2
	ds_read_b32 v3, v0
	v_readlane_b32 s2, v254, 42
	s_waitcnt lgkmcnt(0)
	v_cmp_ne_u32_e32 vcc, 0, v3
	v_mov_b32_e32 v0, s2
	ds_read_b32 v2, v0
	s_cbranch_vccnz .LBB0_946
	s_mov_b32 s2, 1
	s_branch .LBB0_934
